# attention finalize: 2-byte row-per-lane output stores replaced by LDS-staged transpose + 16-byte stores (all four variants)
# speedup vs baseline: 1.0065x; 1.0047x over previous
.LBB0_459:
	s_or_b64 exec, exec, s[8:9]
	v_lshl_add_u32 v76, v235, 2, s10
	s_lshl_b32 s2, s45, 7
	v_or_b32_e32 v74, s44, v235
	s_add_u32 s2, s0, s2
	v_ashrrev_i32_e32 v75, 31, v74
	s_addc_u32 s3, s1, 0
	v_lshlrev_b32_e32 v232, 1, v253
	v_lshl_add_u64 v[74:75], s[6:7], 0, v[74:75]
	v_lshl_add_u64 v[64:65], s[2:3], 0, v[232:233]
	v_lshlrev_b64 v[74:75], 11, v[74:75]
	v_lshl_add_u64 v[74:75], v[64:65], 0, v[74:75]
	v_or_b32_e32 v66, 1, v235
	v_readfirstlane_b32 s68, v74
	v_readfirstlane_b32 s69, v75
	v_readfirstlane_b32 s72, v76
	v_mbcnt_lo_u32_b32 v176, -1, 0
	v_mbcnt_hi_u32_b32 v176, -1, v176
	s_nop 3
	s_sub_i32 s72, s72, 0x1c800
	s_mul_i32 s72, s72, 36
	v_lshrrev_b32_e32 v177, 5, v176
	v_mul_u32_u24_e32 v177, 576, v177
	v_and_b32_e32 v178, 31, v176
	v_lshl_add_u32 v177, v178, 1, v177
	v_add_u32_e32 v177, s72, v177
	v_lshrrev_b32_e32 v179, 3, v176
	v_and_b32_e32 v178, 7, v176
	v_lshlrev_b32_e32 v178, 4, v178
	v_mul_u32_u24_e32 v180, 144, v179
	v_add_u32_e32 v176, v180, v178
	v_add_u32_e32 v176, s72, v176
	v_lshlrev_b32_e32 v179, 11, v179
	v_add_u32_e32 v179, v179, v178
	ds_read_b128 v[160:163], v76 offset:0
	ds_read_b128 v[164:167], v76 offset:32
	ds_read_b128 v[168:171], v76 offset:64
	ds_read_b128 v[172:175], v76 offset:96
	s_waitcnt lgkmcnt(0)
	v_mul_f32_e32 v48, v48, v160
	v_mul_f32_e32 v32, v32, v160
	v_cvt_pk_bf16_f32 v48, v48, v48
	v_cvt_pk_bf16_f32 v32, v32, v32
	ds_write_b16 v177, v48 offset:0
	ds_write_b16 v177, v32 offset:64
	v_mul_f32_e32 v49, v49, v161
	v_mul_f32_e32 v33, v33, v161
	v_cvt_pk_bf16_f32 v49, v49, v49
	v_cvt_pk_bf16_f32 v33, v33, v33
	ds_write_b16 v177, v49 offset:144
	ds_write_b16 v177, v33 offset:208
	v_mul_f32_e32 v50, v50, v162
	v_mul_f32_e32 v34, v34, v162
	v_cvt_pk_bf16_f32 v50, v50, v50
	v_cvt_pk_bf16_f32 v34, v34, v34
	ds_write_b16 v177, v50 offset:288
	ds_write_b16 v177, v34 offset:352
	v_mul_f32_e32 v51, v51, v163
	v_mul_f32_e32 v35, v35, v163
	v_cvt_pk_bf16_f32 v51, v51, v51
	v_cvt_pk_bf16_f32 v35, v35, v35
	ds_write_b16 v177, v51 offset:432
	ds_write_b16 v177, v35 offset:496
	v_mul_f32_e32 v52, v52, v164
	v_mul_f32_e32 v36, v36, v164
	v_cvt_pk_bf16_f32 v52, v52, v52
	v_cvt_pk_bf16_f32 v36, v36, v36
	ds_write_b16 v177, v52 offset:1152
	ds_write_b16 v177, v36 offset:1216
	v_mul_f32_e32 v53, v53, v165
	v_mul_f32_e32 v37, v37, v165
	v_cvt_pk_bf16_f32 v53, v53, v53
	v_cvt_pk_bf16_f32 v37, v37, v37
	ds_write_b16 v177, v53 offset:1296
	ds_write_b16 v177, v37 offset:1360
	v_mul_f32_e32 v54, v54, v166
	v_mul_f32_e32 v38, v38, v166
	v_cvt_pk_bf16_f32 v54, v54, v54
	v_cvt_pk_bf16_f32 v38, v38, v38
	ds_write_b16 v177, v54 offset:1440
	ds_write_b16 v177, v38 offset:1504
	v_mul_f32_e32 v55, v55, v167
	v_mul_f32_e32 v39, v39, v167
	v_cvt_pk_bf16_f32 v55, v55, v55
	v_cvt_pk_bf16_f32 v39, v39, v39
	ds_write_b16 v177, v55 offset:1584
	ds_write_b16 v177, v39 offset:1648
	v_mul_f32_e32 v56, v56, v168
	v_mul_f32_e32 v40, v40, v168
	v_cvt_pk_bf16_f32 v56, v56, v56
	v_cvt_pk_bf16_f32 v40, v40, v40
	ds_write_b16 v177, v56 offset:2304
	ds_write_b16 v177, v40 offset:2368
	v_mul_f32_e32 v57, v57, v169
	v_mul_f32_e32 v41, v41, v169
	v_cvt_pk_bf16_f32 v57, v57, v57
	v_cvt_pk_bf16_f32 v41, v41, v41
	ds_write_b16 v177, v57 offset:2448
	ds_write_b16 v177, v41 offset:2512
	v_mul_f32_e32 v58, v58, v170
	v_mul_f32_e32 v42, v42, v170
	v_cvt_pk_bf16_f32 v58, v58, v58
	v_cvt_pk_bf16_f32 v42, v42, v42
	ds_write_b16 v177, v58 offset:2592
	ds_write_b16 v177, v42 offset:2656
	v_mul_f32_e32 v59, v59, v171
	v_mul_f32_e32 v43, v43, v171
	v_cvt_pk_bf16_f32 v59, v59, v59
	v_cvt_pk_bf16_f32 v43, v43, v43
	ds_write_b16 v177, v59 offset:2736
	ds_write_b16 v177, v43 offset:2800
	v_mul_f32_e32 v60, v60, v172
	v_mul_f32_e32 v44, v44, v172
	v_cvt_pk_bf16_f32 v60, v60, v60
	v_cvt_pk_bf16_f32 v44, v44, v44
	ds_write_b16 v177, v60 offset:3456
	ds_write_b16 v177, v44 offset:3520
	v_mul_f32_e32 v61, v61, v173
	v_mul_f32_e32 v45, v45, v173
	v_cvt_pk_bf16_f32 v61, v61, v61
	v_cvt_pk_bf16_f32 v45, v45, v45
	ds_write_b16 v177, v61 offset:3600
	ds_write_b16 v177, v45 offset:3664
	v_mul_f32_e32 v62, v62, v174
	v_mul_f32_e32 v46, v46, v174
	v_cvt_pk_bf16_f32 v62, v62, v62
	v_cvt_pk_bf16_f32 v46, v46, v46
	ds_write_b16 v177, v62 offset:3744
	ds_write_b16 v177, v46 offset:3808
	v_mul_f32_e32 v63, v63, v175
	v_mul_f32_e32 v47, v47, v175
	v_cvt_pk_bf16_f32 v63, v63, v63
	v_cvt_pk_bf16_f32 v47, v47, v47
	ds_write_b16 v177, v63 offset:3888
	ds_write_b16 v177, v47 offset:3952
	s_waitcnt lgkmcnt(0)
	ds_read_b128 v[160:163], v76 offset:128
	ds_read_b128 v[164:167], v76 offset:160
	ds_read_b128 v[168:171], v76 offset:192
	ds_read_b128 v[172:175], v76 offset:224
	s_waitcnt lgkmcnt(0)
	v_mul_f32_e32 v16, v16, v160
	v_mul_f32_e32 v0, v0, v160
	v_cvt_pk_bf16_f32 v16, v16, v16
	v_cvt_pk_bf16_f32 v0, v0, v0
	ds_write_b16 v177, v16 offset:4608
	ds_write_b16 v177, v0 offset:4672
	v_mul_f32_e32 v17, v17, v161
	v_mul_f32_e32 v1, v1, v161
	v_cvt_pk_bf16_f32 v17, v17, v17
	v_cvt_pk_bf16_f32 v1, v1, v1
	ds_write_b16 v177, v17 offset:4752
	ds_write_b16 v177, v1 offset:4816
	v_mul_f32_e32 v18, v18, v162
	v_mul_f32_e32 v2, v2, v162
	v_cvt_pk_bf16_f32 v18, v18, v18
	v_cvt_pk_bf16_f32 v2, v2, v2
	ds_write_b16 v177, v18 offset:4896
	ds_write_b16 v177, v2 offset:4960
	v_mul_f32_e32 v19, v19, v163
	v_mul_f32_e32 v3, v3, v163
	v_cvt_pk_bf16_f32 v19, v19, v19
	v_cvt_pk_bf16_f32 v3, v3, v3
	ds_write_b16 v177, v19 offset:5040
	ds_write_b16 v177, v3 offset:5104
	v_mul_f32_e32 v20, v20, v164
	v_mul_f32_e32 v4, v4, v164
	v_cvt_pk_bf16_f32 v20, v20, v20
	v_cvt_pk_bf16_f32 v4, v4, v4
	ds_write_b16 v177, v20 offset:5760
	ds_write_b16 v177, v4 offset:5824
	v_mul_f32_e32 v21, v21, v165
	v_mul_f32_e32 v5, v5, v165
	v_cvt_pk_bf16_f32 v21, v21, v21
	v_cvt_pk_bf16_f32 v5, v5, v5
	ds_write_b16 v177, v21 offset:5904
	ds_write_b16 v177, v5 offset:5968
	v_mul_f32_e32 v22, v22, v166
	v_mul_f32_e32 v6, v6, v166
	v_cvt_pk_bf16_f32 v22, v22, v22
	v_cvt_pk_bf16_f32 v6, v6, v6
	ds_write_b16 v177, v22 offset:6048
	ds_write_b16 v177, v6 offset:6112
	v_mul_f32_e32 v23, v23, v167
	v_mul_f32_e32 v7, v7, v167
	v_cvt_pk_bf16_f32 v23, v23, v23
	v_cvt_pk_bf16_f32 v7, v7, v7
	ds_write_b16 v177, v23 offset:6192
	ds_write_b16 v177, v7 offset:6256
	v_mul_f32_e32 v24, v24, v168
	v_mul_f32_e32 v8, v8, v168
	v_cvt_pk_bf16_f32 v24, v24, v24
	v_cvt_pk_bf16_f32 v8, v8, v8
	ds_write_b16 v177, v24 offset:6912
	ds_write_b16 v177, v8 offset:6976
	v_mul_f32_e32 v25, v25, v169
	v_mul_f32_e32 v9, v9, v169
	v_cvt_pk_bf16_f32 v25, v25, v25
	v_cvt_pk_bf16_f32 v9, v9, v9
	ds_write_b16 v177, v25 offset:7056
	ds_write_b16 v177, v9 offset:7120
	v_mul_f32_e32 v26, v26, v170
	v_mul_f32_e32 v10, v10, v170
	v_cvt_pk_bf16_f32 v26, v26, v26
	v_cvt_pk_bf16_f32 v10, v10, v10
	ds_write_b16 v177, v26 offset:7200
	ds_write_b16 v177, v10 offset:7264
	v_mul_f32_e32 v27, v27, v171
	v_mul_f32_e32 v11, v11, v171
	v_cvt_pk_bf16_f32 v27, v27, v27
	v_cvt_pk_bf16_f32 v11, v11, v11
	ds_write_b16 v177, v27 offset:7344
	ds_write_b16 v177, v11 offset:7408
	v_mul_f32_e32 v28, v28, v172
	v_mul_f32_e32 v12, v12, v172
	v_cvt_pk_bf16_f32 v28, v28, v28
	v_cvt_pk_bf16_f32 v12, v12, v12
	ds_write_b16 v177, v28 offset:8064
	ds_write_b16 v177, v12 offset:8128
	v_mul_f32_e32 v29, v29, v173
	v_mul_f32_e32 v13, v13, v173
	v_cvt_pk_bf16_f32 v29, v29, v29
	v_cvt_pk_bf16_f32 v13, v13, v13
	ds_write_b16 v177, v29 offset:8208
	ds_write_b16 v177, v13 offset:8272
	v_mul_f32_e32 v30, v30, v174
	v_mul_f32_e32 v14, v14, v174
	v_cvt_pk_bf16_f32 v30, v30, v30
	v_cvt_pk_bf16_f32 v14, v14, v14
	ds_write_b16 v177, v30 offset:8352
	ds_write_b16 v177, v14 offset:8416
	v_mul_f32_e32 v31, v31, v175
	v_mul_f32_e32 v15, v15, v175
	v_cvt_pk_bf16_f32 v31, v31, v31
	v_cvt_pk_bf16_f32 v15, v15, v15
	ds_write_b16 v177, v31 offset:8496
	ds_write_b16 v177, v15 offset:8560
	s_waitcnt lgkmcnt(0)
	ds_read_b128 v[160:163], v176 offset:0
	ds_read_b128 v[164:167], v176 offset:1152
	ds_read_b128 v[168:171], v176 offset:2304
	ds_read_b128 v[172:175], v176 offset:3456
	s_waitcnt lgkmcnt(0)
	s_add_u32 s70, s68, 0x0
	s_addc_u32 s71, s69, 0
	global_store_dwordx4 v179, v[160:163], s[70:71]
	s_add_u32 s70, s68, 0x4000
	s_addc_u32 s71, s69, 0
	global_store_dwordx4 v179, v[164:167], s[70:71]
	s_add_u32 s70, s68, 0x8000
	s_addc_u32 s71, s69, 0
	global_store_dwordx4 v179, v[168:171], s[70:71]
	s_add_u32 s70, s68, 0xc000
	s_addc_u32 s71, s69, 0
	global_store_dwordx4 v179, v[172:175], s[70:71]
	ds_read_b128 v[160:163], v176 offset:4608
	ds_read_b128 v[164:167], v176 offset:5760
	ds_read_b128 v[168:171], v176 offset:6912
	ds_read_b128 v[172:175], v176 offset:8064
	s_waitcnt lgkmcnt(0)
	s_add_u32 s70, s68, 0x10000
	s_addc_u32 s71, s69, 0
	global_store_dwordx4 v179, v[160:163], s[70:71]
	s_add_u32 s70, s68, 0x14000
	s_addc_u32 s71, s69, 0
	global_store_dwordx4 v179, v[164:167], s[70:71]
	s_add_u32 s70, s68, 0x18000
	s_addc_u32 s71, s69, 0
	global_store_dwordx4 v179, v[168:171], s[70:71]
	s_add_u32 s70, s68, 0x1c000
	s_addc_u32 s71, s69, 0
	global_store_dwordx4 v179, v[172:175], s[70:71]
	s_or_b32 s2, s44, 32
	s_add_i32 s43, s43, s64
	s_cmp_gt_i32 s43, 31
	s_waitcnt lgkmcnt(0)
	s_barrier
	s_cbranch_scc1 .LBB0_494

.LBB0_496:
	s_or_b64 exec, exec, s[4:5]
	v_or_b32_e32 v40, s24, v121
	v_add_u32_e32 v44, s22, v232
	v_ashrrev_i32_e32 v41, 31, v40
	v_lshl_add_u64 v[42:43], s[8:9], 0, v[40:41]
	v_lshlrev_b64 v[42:43], 11, v[42:43]
	v_lshl_add_u64 v[42:43], s[0:1], 0, v[42:43]
	s_lshl_b32 s40, s23, 1
	v_lshl_add_u64 v[42:43], v[42:43], 0, s[40:41]
	v_lshlrev_b32_e32 v232, 1, v120
	v_lshl_add_u64 v[42:43], v[42:43], 0, v[232:233]
	v_readfirstlane_b32 s68, v42
	v_readfirstlane_b32 s69, v43
	v_readfirstlane_b32 s72, v44
	v_mbcnt_lo_u32_b32 v176, -1, 0
	v_mbcnt_hi_u32_b32 v176, -1, v176
	s_nop 3
	s_sub_i32 s72, s72, 0x1c800
	s_mul_i32 s72, s72, 18
	v_lshrrev_b32_e32 v177, 5, v176
	v_mul_u32_u24_e32 v177, 576, v177
	v_and_b32_e32 v178, 31, v176
	v_lshl_add_u32 v177, v178, 1, v177
	v_add_u32_e32 v177, s72, v177
	v_lshrrev_b32_e32 v179, 3, v176
	v_and_b32_e32 v178, 7, v176
	v_lshlrev_b32_e32 v178, 4, v178
	v_mul_u32_u24_e32 v180, 144, v179
	v_add_u32_e32 v176, v180, v178
	v_add_u32_e32 v176, s72, v176
	v_lshlrev_b32_e32 v179, 11, v179
	v_add_u32_e32 v179, v179, v178
	ds_read_b128 v[160:163], v44 offset:0
	ds_read_b128 v[164:167], v44 offset:32
	ds_read_b128 v[168:171], v44 offset:64
	ds_read_b128 v[172:175], v44 offset:96
	s_waitcnt lgkmcnt(0)
	v_mul_f32_e32 v0, v0, v160
	v_mul_f32_e32 v16, v16, v160
	v_cvt_pk_bf16_f32 v0, v0, v0
	v_cvt_pk_bf16_f32 v16, v16, v16
	ds_write_b16 v177, v0 offset:0
	ds_write_b16 v177, v16 offset:64
	v_mul_f32_e32 v1, v1, v161
	v_mul_f32_e32 v17, v17, v161
	v_cvt_pk_bf16_f32 v1, v1, v1
	v_cvt_pk_bf16_f32 v17, v17, v17
	ds_write_b16 v177, v1 offset:144
	ds_write_b16 v177, v17 offset:208
	v_mul_f32_e32 v2, v2, v162
	v_mul_f32_e32 v18, v18, v162
	v_cvt_pk_bf16_f32 v2, v2, v2
	v_cvt_pk_bf16_f32 v18, v18, v18
	ds_write_b16 v177, v2 offset:288
	ds_write_b16 v177, v18 offset:352
	v_mul_f32_e32 v3, v3, v163
	v_mul_f32_e32 v19, v19, v163
	v_cvt_pk_bf16_f32 v3, v3, v3
	v_cvt_pk_bf16_f32 v19, v19, v19
	ds_write_b16 v177, v3 offset:432
	ds_write_b16 v177, v19 offset:496
	v_mul_f32_e32 v4, v4, v164
	v_mul_f32_e32 v20, v20, v164
	v_cvt_pk_bf16_f32 v4, v4, v4
	v_cvt_pk_bf16_f32 v20, v20, v20
	ds_write_b16 v177, v4 offset:1152
	ds_write_b16 v177, v20 offset:1216
	v_mul_f32_e32 v5, v5, v165
	v_mul_f32_e32 v21, v21, v165
	v_cvt_pk_bf16_f32 v5, v5, v5
	v_cvt_pk_bf16_f32 v21, v21, v21
	ds_write_b16 v177, v5 offset:1296
	ds_write_b16 v177, v21 offset:1360
	v_mul_f32_e32 v6, v6, v166
	v_mul_f32_e32 v22, v22, v166
	v_cvt_pk_bf16_f32 v6, v6, v6
	v_cvt_pk_bf16_f32 v22, v22, v22
	ds_write_b16 v177, v6 offset:1440
	ds_write_b16 v177, v22 offset:1504
	v_mul_f32_e32 v7, v7, v167
	v_mul_f32_e32 v23, v23, v167
	v_cvt_pk_bf16_f32 v7, v7, v7
	v_cvt_pk_bf16_f32 v23, v23, v23
	ds_write_b16 v177, v7 offset:1584
	ds_write_b16 v177, v23 offset:1648
	v_mul_f32_e32 v8, v8, v168
	v_mul_f32_e32 v24, v24, v168
	v_cvt_pk_bf16_f32 v8, v8, v8
	v_cvt_pk_bf16_f32 v24, v24, v24
	ds_write_b16 v177, v8 offset:2304
	ds_write_b16 v177, v24 offset:2368
	v_mul_f32_e32 v9, v9, v169
	v_mul_f32_e32 v25, v25, v169
	v_cvt_pk_bf16_f32 v9, v9, v9
	v_cvt_pk_bf16_f32 v25, v25, v25
	ds_write_b16 v177, v9 offset:2448
	ds_write_b16 v177, v25 offset:2512
	v_mul_f32_e32 v10, v10, v170
	v_mul_f32_e32 v26, v26, v170
	v_cvt_pk_bf16_f32 v10, v10, v10
	v_cvt_pk_bf16_f32 v26, v26, v26
	ds_write_b16 v177, v10 offset:2592
	ds_write_b16 v177, v26 offset:2656
	v_mul_f32_e32 v11, v11, v171
	v_mul_f32_e32 v27, v27, v171
	v_cvt_pk_bf16_f32 v11, v11, v11
	v_cvt_pk_bf16_f32 v27, v27, v27
	ds_write_b16 v177, v11 offset:2736
	ds_write_b16 v177, v27 offset:2800
	v_mul_f32_e32 v12, v12, v172
	v_mul_f32_e32 v28, v28, v172
	v_cvt_pk_bf16_f32 v12, v12, v12
	v_cvt_pk_bf16_f32 v28, v28, v28
	ds_write_b16 v177, v12 offset:3456
	ds_write_b16 v177, v28 offset:3520
	v_mul_f32_e32 v13, v13, v173
	v_mul_f32_e32 v29, v29, v173
	v_cvt_pk_bf16_f32 v13, v13, v13
	v_cvt_pk_bf16_f32 v29, v29, v29
	ds_write_b16 v177, v13 offset:3600
	ds_write_b16 v177, v29 offset:3664
	v_mul_f32_e32 v14, v14, v174
	v_mul_f32_e32 v30, v30, v174
	v_cvt_pk_bf16_f32 v14, v14, v14
	v_cvt_pk_bf16_f32 v30, v30, v30
	ds_write_b16 v177, v14 offset:3744
	ds_write_b16 v177, v30 offset:3808
	v_mul_f32_e32 v15, v15, v175
	v_mul_f32_e32 v31, v31, v175
	v_cvt_pk_bf16_f32 v15, v15, v15
	v_cvt_pk_bf16_f32 v31, v31, v31
	ds_write_b16 v177, v15 offset:3888
	ds_write_b16 v177, v31 offset:3952
	s_waitcnt lgkmcnt(0)
	ds_read_b128 v[160:163], v176 offset:0
	ds_read_b128 v[164:167], v176 offset:1152
	ds_read_b128 v[168:171], v176 offset:2304
	ds_read_b128 v[172:175], v176 offset:3456
	s_waitcnt lgkmcnt(0)
	s_add_u32 s70, s68, 0x0
	s_addc_u32 s71, s69, 0
	global_store_dwordx4 v179, v[160:163], s[70:71] offset:512
	s_add_u32 s70, s68, 0x4000
	s_addc_u32 s71, s69, 0
	global_store_dwordx4 v179, v[164:167], s[70:71] offset:512
	s_add_u32 s70, s68, 0x8000
	s_addc_u32 s71, s69, 0
	global_store_dwordx4 v179, v[168:171], s[70:71] offset:512
	s_add_u32 s70, s68, 0xc000
	s_addc_u32 s71, s69, 0
	global_store_dwordx4 v179, v[172:175], s[70:71] offset:512
	s_add_i32 s21, s21, s64
	s_add_i32 s20, s20, s64
	s_add_i32 s18, s18, s19
	s_cmp_gt_i32 s21, 63
	s_waitcnt lgkmcnt(0)
	s_barrier
	s_cbranch_scc1 .LBB0_598

.LBB0_599:
	s_or_b64 exec, exec, s[4:5]
	v_readlane_b32 s2, v255, 11
	s_lshl_b32 s2, s2, 6
	v_or_b32_e32 v42, s86, v124
	v_or_b32_e32 v40, s2, v42
	v_lshl_add_u32 v43, v124, 2, s88
	v_ashrrev_i32_e32 v41, 31, v40
	v_lshl_add_u64 v[40:41], s[78:79], 0, v[40:41]
	v_lshlrev_b64 v[40:41], 11, v[40:41]
	v_readlane_b32 s4, v254, 32
	v_readlane_b32 s3, v255, 10
	v_lshl_add_u64 v[40:41], s[0:1], 0, v[40:41]
	v_readlane_b32 s5, v254, 33
	s_lshl_b32 s4, s3, 1
	v_lshl_add_u64 v[40:41], v[40:41], 0, s[4:5]
	v_lshlrev_b32_e32 v232, 1, v125
	v_lshl_add_u64 v[40:41], v[40:41], 0, v[232:233]
	v_or_b32_e32 v32, 1, v124
	s_or_b32 s3, s2, s86
	v_readfirstlane_b32 s68, v40
	v_readfirstlane_b32 s69, v41
	v_readfirstlane_b32 s72, v43
	v_mbcnt_lo_u32_b32 v176, -1, 0
	v_mbcnt_hi_u32_b32 v176, -1, v176
	s_nop 3
	s_sub_i32 s72, s72, 0x1c800
	s_mul_i32 s72, s72, 18
	v_lshrrev_b32_e32 v177, 5, v176
	v_mul_u32_u24_e32 v177, 576, v177
	v_and_b32_e32 v178, 31, v176
	v_lshl_add_u32 v177, v178, 1, v177
	v_add_u32_e32 v177, s72, v177
	v_lshrrev_b32_e32 v179, 3, v176
	v_and_b32_e32 v178, 7, v176
	v_lshlrev_b32_e32 v178, 4, v178
	v_mul_u32_u24_e32 v180, 144, v179
	v_add_u32_e32 v176, v180, v178
	v_add_u32_e32 v176, s72, v176
	v_lshlrev_b32_e32 v179, 11, v179
	v_add_u32_e32 v179, v179, v178
	ds_read_b128 v[160:163], v43 offset:0
	ds_read_b128 v[164:167], v43 offset:32
	ds_read_b128 v[168:171], v43 offset:64
	ds_read_b128 v[172:175], v43 offset:96
	s_waitcnt lgkmcnt(0)
	v_mul_f32_e32 v0, v0, v160
	v_mul_f32_e32 v16, v16, v160
	v_cvt_pk_bf16_f32 v0, v0, v0
	v_cvt_pk_bf16_f32 v16, v16, v16
	ds_write_b16 v177, v0 offset:0
	ds_write_b16 v177, v16 offset:64
	v_mul_f32_e32 v1, v1, v161
	v_mul_f32_e32 v17, v17, v161
	v_cvt_pk_bf16_f32 v1, v1, v1
	v_cvt_pk_bf16_f32 v17, v17, v17
	ds_write_b16 v177, v1 offset:144
	ds_write_b16 v177, v17 offset:208
	v_mul_f32_e32 v2, v2, v162
	v_mul_f32_e32 v18, v18, v162
	v_cvt_pk_bf16_f32 v2, v2, v2
	v_cvt_pk_bf16_f32 v18, v18, v18
	ds_write_b16 v177, v2 offset:288
	ds_write_b16 v177, v18 offset:352
	v_mul_f32_e32 v3, v3, v163
	v_mul_f32_e32 v19, v19, v163
	v_cvt_pk_bf16_f32 v3, v3, v3
	v_cvt_pk_bf16_f32 v19, v19, v19
	ds_write_b16 v177, v3 offset:432
	ds_write_b16 v177, v19 offset:496
	v_mul_f32_e32 v4, v4, v164
	v_mul_f32_e32 v20, v20, v164
	v_cvt_pk_bf16_f32 v4, v4, v4
	v_cvt_pk_bf16_f32 v20, v20, v20
	ds_write_b16 v177, v4 offset:1152
	ds_write_b16 v177, v20 offset:1216
	v_mul_f32_e32 v5, v5, v165
	v_mul_f32_e32 v21, v21, v165
	v_cvt_pk_bf16_f32 v5, v5, v5
	v_cvt_pk_bf16_f32 v21, v21, v21
	ds_write_b16 v177, v5 offset:1296
	ds_write_b16 v177, v21 offset:1360
	v_mul_f32_e32 v6, v6, v166
	v_mul_f32_e32 v22, v22, v166
	v_cvt_pk_bf16_f32 v6, v6, v6
	v_cvt_pk_bf16_f32 v22, v22, v22
	ds_write_b16 v177, v6 offset:1440
	ds_write_b16 v177, v22 offset:1504
	v_mul_f32_e32 v7, v7, v167
	v_mul_f32_e32 v23, v23, v167
	v_cvt_pk_bf16_f32 v7, v7, v7
	v_cvt_pk_bf16_f32 v23, v23, v23
	ds_write_b16 v177, v7 offset:1584
	ds_write_b16 v177, v23 offset:1648
	v_mul_f32_e32 v8, v8, v168
	v_mul_f32_e32 v24, v24, v168
	v_cvt_pk_bf16_f32 v8, v8, v8
	v_cvt_pk_bf16_f32 v24, v24, v24
	ds_write_b16 v177, v8 offset:2304
	ds_write_b16 v177, v24 offset:2368
	v_mul_f32_e32 v9, v9, v169
	v_mul_f32_e32 v25, v25, v169
	v_cvt_pk_bf16_f32 v9, v9, v9
	v_cvt_pk_bf16_f32 v25, v25, v25
	ds_write_b16 v177, v9 offset:2448
	ds_write_b16 v177, v25 offset:2512
	v_mul_f32_e32 v10, v10, v170
	v_mul_f32_e32 v26, v26, v170
	v_cvt_pk_bf16_f32 v10, v10, v10
	v_cvt_pk_bf16_f32 v26, v26, v26
	ds_write_b16 v177, v10 offset:2592
	ds_write_b16 v177, v26 offset:2656
	v_mul_f32_e32 v11, v11, v171
	v_mul_f32_e32 v27, v27, v171
	v_cvt_pk_bf16_f32 v11, v11, v11
	v_cvt_pk_bf16_f32 v27, v27, v27
	ds_write_b16 v177, v11 offset:2736
	ds_write_b16 v177, v27 offset:2800
	v_mul_f32_e32 v12, v12, v172
	v_mul_f32_e32 v28, v28, v172
	v_cvt_pk_bf16_f32 v12, v12, v12
	v_cvt_pk_bf16_f32 v28, v28, v28
	ds_write_b16 v177, v12 offset:3456
	ds_write_b16 v177, v28 offset:3520
	v_mul_f32_e32 v13, v13, v173
	v_mul_f32_e32 v29, v29, v173
	v_cvt_pk_bf16_f32 v13, v13, v13
	v_cvt_pk_bf16_f32 v29, v29, v29
	ds_write_b16 v177, v13 offset:3600
	ds_write_b16 v177, v29 offset:3664
	v_mul_f32_e32 v14, v14, v174
	v_mul_f32_e32 v30, v30, v174
	v_cvt_pk_bf16_f32 v14, v14, v14
	v_cvt_pk_bf16_f32 v30, v30, v30
	ds_write_b16 v177, v14 offset:3744
	ds_write_b16 v177, v30 offset:3808
	v_mul_f32_e32 v15, v15, v175
	v_mul_f32_e32 v31, v31, v175
	v_cvt_pk_bf16_f32 v15, v15, v15
	v_cvt_pk_bf16_f32 v31, v31, v31
	ds_write_b16 v177, v15 offset:3888
	ds_write_b16 v177, v31 offset:3952
	s_waitcnt lgkmcnt(0)
	ds_read_b128 v[160:163], v176 offset:0
	ds_read_b128 v[164:167], v176 offset:1152
	ds_read_b128 v[168:171], v176 offset:2304
	ds_read_b128 v[172:175], v176 offset:3456
	s_waitcnt lgkmcnt(0)
	s_add_u32 s70, s68, 0x0
	s_addc_u32 s71, s69, 0
	global_store_dwordx4 v179, v[160:163], s[70:71] offset:1024
	s_add_u32 s70, s68, 0x4000
	s_addc_u32 s71, s69, 0
	global_store_dwordx4 v179, v[164:167], s[70:71] offset:1024
	s_add_u32 s70, s68, 0x20000
	s_addc_u32 s71, s69, 0
	global_store_dwordx4 v179, v[168:171], s[70:71] offset:1024
	s_add_u32 s70, s68, 0x24000
	s_addc_u32 s71, s69, 0
	global_store_dwordx4 v179, v[172:175], s[70:71] offset:1024
	s_or_b32 s2, s2, 64
	v_readlane_b32 s9, v254, 37
	v_readlane_b32 s8, v254, 36
	v_readlane_b32 s10, v254, 38
	v_readlane_b32 s11, v254, 39
	v_readlane_b32 s12, v254, 40
	v_readlane_b32 s13, v254, 41
	v_readlane_b32 s14, v254, 42
	v_readlane_b32 s15, v254, 43
	v_readlane_b32 s16, v254, 44
	v_readlane_b32 s17, v254, 45
	v_readlane_b32 s18, v254, 46
	v_readlane_b32 s19, v254, 47
	s_mov_b32 s9, s5
	v_readlane_b32 s6, v254, 34
	v_readlane_b32 s7, v254, 35
	v_writelane_b32 v254, s8, 32
	v_writelane_b32 v254, s9, 33
	v_writelane_b32 v254, s10, 34
	v_writelane_b32 v254, s11, 35
	v_writelane_b32 v254, s12, 36
	v_writelane_b32 v254, s13, 37
	v_writelane_b32 v254, s14, 38
	v_writelane_b32 v254, s15, 39
	v_writelane_b32 v254, s16, 40
	v_writelane_b32 v254, s17, 41
	v_writelane_b32 v254, s18, 42
	v_writelane_b32 v254, s19, 43
	v_writelane_b32 v254, s20, 44
	v_readlane_b32 s64, v255, 7
	v_readlane_b32 s2, v255, 3
	v_writelane_b32 v254, s21, 45
	s_add_i32 s2, s2, s64
	v_writelane_b32 v254, s22, 46
	v_writelane_b32 v255, s2, 3
	v_writelane_b32 v254, s23, 47
	v_readlane_b32 s8, v255, 9
	v_readlane_b32 s2, v255, 6
	s_add_i32 s77, s77, s64
	s_add_i32 s8, s8, s2
	v_readlane_b32 s86, v254, 50
	s_cmp_gt_i32 s77, 63
	v_readlane_b32 s87, v254, 51
	v_readlane_b32 s88, v254, 52
	s_movk_i32 s76, 0xfc00
	s_movk_i32 s78, 0x400
	s_mov_b32 s84, 0xf800000
	s_movk_i32 s85, 0x300
	s_movk_i32 s79, 0x180
	s_movk_i32 s80, 0x200
	v_readlane_b32 s89, v254, 54
	s_movk_i32 s46, 0xe800
	s_mov_b32 s66, 0xc2800000
	v_readlane_b32 s56, v255, 8
	s_waitcnt lgkmcnt(0)
	s_barrier
	s_cbranch_scc1 .LBB0_692

.LBB0_695:
	s_or_b64 exec, exec, s[10:11]
	v_or_b32_e32 v32, s22, v83
	v_ashrrev_i32_e32 v33, 31, v32
	v_add_u32_e32 v44, s17, v232
	v_lshlrev_b64 v[42:43], s16, v[32:33]
	v_lshl_add_u64 v[42:43], v[42:43], 0, s[6:7]
	v_lshlrev_b64 v[42:43], 13, v[42:43]
	v_lshl_add_u64 v[42:43], s[74:75], 0, v[42:43]
	v_lshl_add_u64 v[42:43], v[42:43], 0, s[8:9]
	s_lshl_b32 s40, s23, 1
	v_lshl_add_u64 v[42:43], v[42:43], 0, s[40:41]
	v_lshlrev_b32_e32 v232, 1, v82
	v_lshl_add_u64 v[42:43], v[42:43], 0, v[232:233]
	v_readfirstlane_b32 s68, v42
	v_readfirstlane_b32 s69, v43
	v_readfirstlane_b32 s72, v44
	v_mbcnt_lo_u32_b32 v176, -1, 0
	v_mbcnt_hi_u32_b32 v176, -1, v176
	s_nop 3
	s_sub_i32 s72, s72, 0x1c800
	s_mul_i32 s72, s72, 18
	v_lshrrev_b32_e32 v177, 5, v176
	v_mul_u32_u24_e32 v177, 576, v177
	v_and_b32_e32 v178, 31, v176
	v_lshl_add_u32 v177, v178, 1, v177
	v_add_u32_e32 v177, s72, v177
	v_lshrrev_b32_e32 v179, 3, v176
	v_and_b32_e32 v178, 7, v176
	v_lshlrev_b32_e32 v178, 4, v178
	v_mul_u32_u24_e32 v180, 144, v179
	v_add_u32_e32 v176, v180, v178
	v_add_u32_e32 v176, s72, v176
	s_add_i32 s73, s16, 13
	v_lshlrev_b32_e32 v179, s73, v179
	v_add_u32_e32 v179, v179, v178
	ds_read_b128 v[160:163], v44 offset:0
	ds_read_b128 v[164:167], v44 offset:32
	ds_read_b128 v[168:171], v44 offset:64
	ds_read_b128 v[172:175], v44 offset:96
	s_waitcnt lgkmcnt(0)
	v_mul_f32_e32 v0, v0, v160
	v_mul_f32_e32 v16, v16, v160
	v_cvt_pk_bf16_f32 v0, v0, v0
	v_cvt_pk_bf16_f32 v16, v16, v16
	ds_write_b16 v177, v0 offset:0
	ds_write_b16 v177, v16 offset:64
	v_mul_f32_e32 v1, v1, v161
	v_mul_f32_e32 v17, v17, v161
	v_cvt_pk_bf16_f32 v1, v1, v1
	v_cvt_pk_bf16_f32 v17, v17, v17
	ds_write_b16 v177, v1 offset:144
	ds_write_b16 v177, v17 offset:208
	v_mul_f32_e32 v2, v2, v162
	v_mul_f32_e32 v18, v18, v162
	v_cvt_pk_bf16_f32 v2, v2, v2
	v_cvt_pk_bf16_f32 v18, v18, v18
	ds_write_b16 v177, v2 offset:288
	ds_write_b16 v177, v18 offset:352
	v_mul_f32_e32 v3, v3, v163
	v_mul_f32_e32 v19, v19, v163
	v_cvt_pk_bf16_f32 v3, v3, v3
	v_cvt_pk_bf16_f32 v19, v19, v19
	ds_write_b16 v177, v3 offset:432
	ds_write_b16 v177, v19 offset:496
	v_mul_f32_e32 v4, v4, v164
	v_mul_f32_e32 v20, v20, v164
	v_cvt_pk_bf16_f32 v4, v4, v4
	v_cvt_pk_bf16_f32 v20, v20, v20
	ds_write_b16 v177, v4 offset:1152
	ds_write_b16 v177, v20 offset:1216
	v_mul_f32_e32 v5, v5, v165
	v_mul_f32_e32 v21, v21, v165
	v_cvt_pk_bf16_f32 v5, v5, v5
	v_cvt_pk_bf16_f32 v21, v21, v21
	ds_write_b16 v177, v5 offset:1296
	ds_write_b16 v177, v21 offset:1360
	v_mul_f32_e32 v6, v6, v166
	v_mul_f32_e32 v22, v22, v166
	v_cvt_pk_bf16_f32 v6, v6, v6
	v_cvt_pk_bf16_f32 v22, v22, v22
	ds_write_b16 v177, v6 offset:1440
	ds_write_b16 v177, v22 offset:1504
	v_mul_f32_e32 v7, v7, v167
	v_mul_f32_e32 v23, v23, v167
	v_cvt_pk_bf16_f32 v7, v7, v7
	v_cvt_pk_bf16_f32 v23, v23, v23
	ds_write_b16 v177, v7 offset:1584
	ds_write_b16 v177, v23 offset:1648
	v_mul_f32_e32 v8, v8, v168
	v_mul_f32_e32 v24, v24, v168
	v_cvt_pk_bf16_f32 v8, v8, v8
	v_cvt_pk_bf16_f32 v24, v24, v24
	ds_write_b16 v177, v8 offset:2304
	ds_write_b16 v177, v24 offset:2368
	v_mul_f32_e32 v9, v9, v169
	v_mul_f32_e32 v25, v25, v169
	v_cvt_pk_bf16_f32 v9, v9, v9
	v_cvt_pk_bf16_f32 v25, v25, v25
	ds_write_b16 v177, v9 offset:2448
	ds_write_b16 v177, v25 offset:2512
	v_mul_f32_e32 v10, v10, v170
	v_mul_f32_e32 v26, v26, v170
	v_cvt_pk_bf16_f32 v10, v10, v10
	v_cvt_pk_bf16_f32 v26, v26, v26
	ds_write_b16 v177, v10 offset:2592
	ds_write_b16 v177, v26 offset:2656
	v_mul_f32_e32 v11, v11, v171
	v_mul_f32_e32 v27, v27, v171
	v_cvt_pk_bf16_f32 v11, v11, v11
	v_cvt_pk_bf16_f32 v27, v27, v27
	ds_write_b16 v177, v11 offset:2736
	ds_write_b16 v177, v27 offset:2800
	v_mul_f32_e32 v12, v12, v172
	v_mul_f32_e32 v28, v28, v172
	v_cvt_pk_bf16_f32 v12, v12, v12
	v_cvt_pk_bf16_f32 v28, v28, v28
	ds_write_b16 v177, v12 offset:3456
	ds_write_b16 v177, v28 offset:3520
	v_mul_f32_e32 v13, v13, v173
	v_mul_f32_e32 v29, v29, v173
	v_cvt_pk_bf16_f32 v13, v13, v13
	v_cvt_pk_bf16_f32 v29, v29, v29
	ds_write_b16 v177, v13 offset:3600
	ds_write_b16 v177, v29 offset:3664
	v_mul_f32_e32 v14, v14, v174
	v_mul_f32_e32 v30, v30, v174
	v_cvt_pk_bf16_f32 v14, v14, v14
	v_cvt_pk_bf16_f32 v30, v30, v30
	ds_write_b16 v177, v14 offset:3744
	ds_write_b16 v177, v30 offset:3808
	v_mul_f32_e32 v15, v15, v175
	v_mul_f32_e32 v31, v31, v175
	v_cvt_pk_bf16_f32 v15, v15, v15
	v_cvt_pk_bf16_f32 v31, v31, v31
	ds_write_b16 v177, v15 offset:3888
	ds_write_b16 v177, v31 offset:3952
	s_waitcnt lgkmcnt(0)
	ds_read_b128 v[160:163], v176 offset:0
	ds_read_b128 v[164:167], v176 offset:1152
	ds_read_b128 v[168:171], v176 offset:2304
	ds_read_b128 v[172:175], v176 offset:3456
	s_waitcnt lgkmcnt(0)
	s_mov_b32 s70, 0
	s_lshl_b32 s70, s70, s73
	s_add_u32 s70, s68, s70
	s_addc_u32 s71, s69, 0
	global_store_dwordx4 v179, v[160:163], s[70:71] offset:3392
	s_mov_b32 s70, 8
	s_lshl_b32 s70, s70, s73
	s_add_u32 s70, s68, s70
	s_addc_u32 s71, s69, 0
	global_store_dwordx4 v179, v[164:167], s[70:71] offset:3392
	s_mov_b32 s70, 16
	s_lshl_b32 s70, s70, s73
	s_add_u32 s70, s68, s70
	s_addc_u32 s71, s69, 0
	global_store_dwordx4 v179, v[168:171], s[70:71] offset:3392
	s_mov_b32 s70, 24
	s_lshl_b32 s70, s70, s73
	s_add_u32 s70, s68, s70
	s_addc_u32 s71, s69, 0
	global_store_dwordx4 v179, v[172:175], s[70:71] offset:3392
	s_mov_b32 s9, s41
	v_writelane_b32 v254, s8, 32
	v_writelane_b32 v254, s9, 33
	v_writelane_b32 v254, s10, 34
	v_writelane_b32 v254, s11, 35
	v_writelane_b32 v254, s12, 36
	v_writelane_b32 v254, s13, 37
	v_writelane_b32 v254, s14, 38
	v_writelane_b32 v254, s15, 39
	v_writelane_b32 v254, s16, 40
	v_writelane_b32 v254, s17, 41
	v_writelane_b32 v254, s18, 42
	v_writelane_b32 v254, s19, 43
	v_writelane_b32 v254, s20, 44
	v_writelane_b32 v254, s21, 45
	v_writelane_b32 v254, s22, 46
	v_writelane_b32 v254, s23, 47
	s_add_i32 s38, s38, s64
	s_add_i32 s15, s15, s64
	s_cmpk_lt_i32 s38, 0xc0
	s_waitcnt lgkmcnt(0)
	s_barrier
	s_cbranch_scc0 .LBB0_791
